# m23 + step A MFMA/relu section re-pipelined by hand: q fragments read three heads ahead into four rotating register sets, two result sets so each head's relu/fmac runs between the next head's MFMAs (s
# speedup vs baseline: 1.0036x; 1.0000x over previous
.LBB0_1296:
	s_add_i32 s8, s3, s17
	s_add_i32 s0, s18, 1
	s_add_i32 s9, s8, 8
	s_cmp_lt_i32 s0, s13
	s_cselect_b64 s[0:1], -1, 0
	s_and_b64 vcc, s[0:1], exec
	s_cselect_b32 s10, s9, s8
	s_add_i32 s9, s8, 16
	s_cmp_lt_i32 s18, s14
	s_cselect_b32 s9, s9, s8
	s_add_i32 s8, s8, 24
	s_cmp_lt_i32 s18, s15
	s_cselect_b32 s11, s8, s9
	s_lshl_b32 s68, s9, 4
	s_lshl_b64 s[8:9], s[68:69], 7
	ds_read_b128 v[200:203], v173
	ds_read_b128 v[204:207], v173 offset:1024
	ds_read_b128 v[22:25], v174
	ds_read_b128 v[18:21], v174 offset:1024
	ds_read_b128 v[208:211], v173 offset:2048
	ds_read_b128 v[212:215], v173 offset:3072
	ds_read_b128 v[216:219], v173 offset:4096
	ds_read_b128 v[226:229], v173 offset:5120
	s_waitcnt vmcnt(0) lgkmcnt(6)
	v_mfma_f32_16x16x32_bf16 v[230:233], v[6:9], v[200:203], 0
	ds_read_b128 v[178:181], v173 offset:6144
	ds_read_b128 v[182:185], v173 offset:7168
	v_mfma_f32_16x16x32_bf16 v[234:237], v[14:17], v[200:203], 0
	v_mfma_f32_16x16x32_bf16 v[230:233], v[2:5], v[204:207], v[230:233]
	v_mov_b32_e32 v34, 0
	v_mov_b32_e32 v35, 0
	v_mov_b32_e32 v32, 0
	v_mov_b32_e32 v33, 0
	v_mfma_f32_16x16x32_bf16 v[234:237], v[10:13], v[204:207], v[234:237]
	v_mov_b32_e32 v30, 0
	v_mov_b32_e32 v31, 0
	v_mov_b32_e32 v28, 0
	v_mov_b32_e32 v29, 0
	s_waitcnt lgkmcnt(4)
	v_mfma_f32_16x16x32_bf16 v[238:241], v[6:9], v[208:211], 0
	ds_read_b128 v[200:203], v173 offset:8192
	ds_read_b128 v[204:207], v173 offset:9216
	v_max_i32_e32 v250, 0, v230
	v_fmac_f32_e32 v34, v250, v22
	v_max_i32_e32 v225, 0, v231
	v_fmac_f32_e32 v35, v225, v22
	v_mfma_f32_16x16x32_bf16 v[242:245], v[14:17], v[208:211], 0
	v_max_i32_e32 v250, 0, v232
	v_fmac_f32_e32 v32, v250, v22
	v_max_i32_e32 v225, 0, v233
	v_fmac_f32_e32 v33, v225, v22
	v_mfma_f32_16x16x32_bf16 v[238:241], v[2:5], v[212:215], v[238:241]
	v_max_i32_e32 v250, 0, v234
	v_fmac_f32_e32 v30, v250, v22
	v_max_i32_e32 v225, 0, v235
	v_fmac_f32_e32 v31, v225, v22
	v_mfma_f32_16x16x32_bf16 v[242:245], v[10:13], v[212:215], v[242:245]
	v_max_i32_e32 v250, 0, v236
	v_fmac_f32_e32 v28, v250, v22
	v_max_i32_e32 v225, 0, v237
	v_fmac_f32_e32 v29, v225, v22
	s_waitcnt lgkmcnt(4)
	v_mfma_f32_16x16x32_bf16 v[230:233], v[6:9], v[216:219], 0
	ds_read_b128 v[208:211], v173 offset:10240
	ds_read_b128 v[212:215], v173 offset:11264
	v_max_i32_e32 v250, 0, v238
	v_fmac_f32_e32 v34, v250, v23
	v_max_i32_e32 v225, 0, v239
	v_fmac_f32_e32 v35, v225, v23
	v_mfma_f32_16x16x32_bf16 v[234:237], v[14:17], v[216:219], 0
	v_max_i32_e32 v250, 0, v240
	v_fmac_f32_e32 v32, v250, v23
	v_max_i32_e32 v225, 0, v241
	v_fmac_f32_e32 v33, v225, v23
	v_mfma_f32_16x16x32_bf16 v[230:233], v[2:5], v[226:229], v[230:233]
	v_max_i32_e32 v250, 0, v242
	v_fmac_f32_e32 v30, v250, v23
	v_max_i32_e32 v225, 0, v243
	v_fmac_f32_e32 v31, v225, v23
	v_mfma_f32_16x16x32_bf16 v[234:237], v[10:13], v[226:229], v[234:237]
	v_max_i32_e32 v250, 0, v244
	v_fmac_f32_e32 v28, v250, v23
	v_max_i32_e32 v225, 0, v245
	v_fmac_f32_e32 v29, v225, v23
	s_waitcnt lgkmcnt(4)
	v_mfma_f32_16x16x32_bf16 v[238:241], v[6:9], v[178:181], 0
	ds_read_b128 v[216:219], v173 offset:12288
	ds_read_b128 v[226:229], v173 offset:13312
	v_max_i32_e32 v250, 0, v230
	v_fmac_f32_e32 v34, v250, v24
	v_max_i32_e32 v225, 0, v231
	v_fmac_f32_e32 v35, v225, v24
	v_mfma_f32_16x16x32_bf16 v[242:245], v[14:17], v[178:181], 0
	v_max_i32_e32 v250, 0, v232
	v_fmac_f32_e32 v32, v250, v24
	v_max_i32_e32 v225, 0, v233
	v_fmac_f32_e32 v33, v225, v24
	v_mfma_f32_16x16x32_bf16 v[238:241], v[2:5], v[182:185], v[238:241]
	v_max_i32_e32 v250, 0, v234
	v_fmac_f32_e32 v30, v250, v24
	v_max_i32_e32 v225, 0, v235
	v_fmac_f32_e32 v31, v225, v24
	v_mfma_f32_16x16x32_bf16 v[242:245], v[10:13], v[182:185], v[242:245]
	v_max_i32_e32 v250, 0, v236
	v_fmac_f32_e32 v28, v250, v24
	v_max_i32_e32 v225, 0, v237
	v_fmac_f32_e32 v29, v225, v24
	s_waitcnt lgkmcnt(4)
	v_mfma_f32_16x16x32_bf16 v[230:233], v[6:9], v[200:203], 0
	ds_read_b128 v[178:181], v173 offset:14336
	ds_read_b128 v[182:185], v173 offset:15360
	v_max_i32_e32 v250, 0, v238
	v_fmac_f32_e32 v34, v250, v25
	v_max_i32_e32 v225, 0, v239
	v_fmac_f32_e32 v35, v225, v25
	v_mfma_f32_16x16x32_bf16 v[234:237], v[14:17], v[200:203], 0
	v_max_i32_e32 v250, 0, v240
	v_fmac_f32_e32 v32, v250, v25
	v_max_i32_e32 v225, 0, v241
	v_fmac_f32_e32 v33, v225, v25
	v_mfma_f32_16x16x32_bf16 v[230:233], v[2:5], v[204:207], v[230:233]
	v_max_i32_e32 v250, 0, v242
	v_fmac_f32_e32 v30, v250, v25
	v_max_i32_e32 v225, 0, v243
	v_fmac_f32_e32 v31, v225, v25
	v_mfma_f32_16x16x32_bf16 v[234:237], v[10:13], v[204:207], v[234:237]
	v_max_i32_e32 v250, 0, v244
	v_fmac_f32_e32 v28, v250, v25
	v_max_i32_e32 v225, 0, v245
	v_fmac_f32_e32 v29, v225, v25
	s_waitcnt lgkmcnt(4)
	v_mfma_f32_16x16x32_bf16 v[238:241], v[6:9], v[208:211], 0
	v_max_i32_e32 v250, 0, v230
	v_fmac_f32_e32 v34, v250, v18
	v_max_i32_e32 v225, 0, v231
	v_fmac_f32_e32 v35, v225, v18
	v_mfma_f32_16x16x32_bf16 v[242:245], v[14:17], v[208:211], 0
	v_max_i32_e32 v250, 0, v232
	v_fmac_f32_e32 v32, v250, v18
	v_max_i32_e32 v225, 0, v233
	v_fmac_f32_e32 v33, v225, v18
	v_mfma_f32_16x16x32_bf16 v[238:241], v[2:5], v[212:215], v[238:241]
	v_max_i32_e32 v250, 0, v234
	v_fmac_f32_e32 v30, v250, v18
	v_max_i32_e32 v225, 0, v235
	v_fmac_f32_e32 v31, v225, v18
	v_mfma_f32_16x16x32_bf16 v[242:245], v[10:13], v[212:215], v[242:245]
	v_max_i32_e32 v250, 0, v236
	v_fmac_f32_e32 v28, v250, v18
	v_max_i32_e32 v225, 0, v237
	v_fmac_f32_e32 v29, v225, v18
	s_waitcnt lgkmcnt(2)
	v_mfma_f32_16x16x32_bf16 v[230:233], v[6:9], v[216:219], 0
	v_max_i32_e32 v250, 0, v238
	v_fmac_f32_e32 v34, v250, v19
	v_max_i32_e32 v225, 0, v239
	v_fmac_f32_e32 v35, v225, v19
	v_mfma_f32_16x16x32_bf16 v[234:237], v[14:17], v[216:219], 0
	v_max_i32_e32 v250, 0, v240
	v_fmac_f32_e32 v32, v250, v19
	v_max_i32_e32 v225, 0, v241
	v_fmac_f32_e32 v33, v225, v19
	v_mfma_f32_16x16x32_bf16 v[230:233], v[2:5], v[226:229], v[230:233]
	v_max_i32_e32 v250, 0, v242
	v_fmac_f32_e32 v30, v250, v19
	v_max_i32_e32 v225, 0, v243
	v_fmac_f32_e32 v31, v225, v19
	v_mfma_f32_16x16x32_bf16 v[234:237], v[10:13], v[226:229], v[234:237]
	v_max_i32_e32 v250, 0, v244
	v_fmac_f32_e32 v28, v250, v19
	v_max_i32_e32 v225, 0, v245
	v_fmac_f32_e32 v29, v225, v19
	s_waitcnt lgkmcnt(0)
	v_mfma_f32_16x16x32_bf16 v[238:241], v[6:9], v[178:181], 0
	v_max_i32_e32 v250, 0, v230
	v_fmac_f32_e32 v34, v250, v20
	v_max_i32_e32 v225, 0, v231
	v_fmac_f32_e32 v35, v225, v20
	v_mfma_f32_16x16x32_bf16 v[242:245], v[14:17], v[178:181], 0
	v_max_i32_e32 v250, 0, v232
	v_fmac_f32_e32 v32, v250, v20
	v_max_i32_e32 v225, 0, v233
	v_fmac_f32_e32 v33, v225, v20
	v_mfma_f32_16x16x32_bf16 v[238:241], v[2:5], v[182:185], v[238:241]
	v_max_i32_e32 v250, 0, v234
	v_fmac_f32_e32 v30, v250, v20
	v_max_i32_e32 v225, 0, v235
	v_fmac_f32_e32 v31, v225, v20
	v_mfma_f32_16x16x32_bf16 v[242:245], v[10:13], v[182:185], v[242:245]
	v_max_i32_e32 v250, 0, v236
	v_fmac_f32_e32 v28, v250, v20
	v_max_i32_e32 v225, 0, v237
	v_fmac_f32_e32 v29, v225, v20
	v_max_i32_e32 v250, 0, v238
	v_fmac_f32_e32 v34, v250, v21
	v_max_i32_e32 v225, 0, v239
	v_fmac_f32_e32 v35, v225, v21
	v_max_i32_e32 v250, 0, v240
	v_fmac_f32_e32 v32, v250, v21
	v_max_i32_e32 v225, 0, v241
	v_fmac_f32_e32 v33, v225, v21
	v_max_i32_e32 v250, 0, v242
	v_fmac_f32_e32 v30, v250, v21
	v_max_i32_e32 v225, 0, v243
	v_fmac_f32_e32 v31, v225, v21
	v_max_i32_e32 v250, 0, v244
	v_fmac_f32_e32 v28, v250, v21
	v_max_i32_e32 v225, 0, v245
	v_fmac_f32_e32 v29, v225, v21
	v_lshl_add_u64 v[2:3], v[26:27], 0, s[8:9]
	s_lshl_b32 s8, s11, 4
	s_ashr_i32 s9, s8, 31
	s_lshl_b64 s[8:9], s[8:9], 7
	v_lshl_add_u64 v[10:11], v[26:27], 0, s[8:9]
	global_load_dwordx4 v[6:9], v[2:3], off
	s_nop 0
	global_load_dwordx4 v[2:5], v[2:3], off offset:64
	s_nop 0
	global_load_dwordx4 v[14:17], v[10:11], off
	s_nop 0
	global_load_dwordx4 v[10:13], v[10:11], off offset:64
	s_cmp_eq_u32 s10, s12
	v_ashrrev_i32_e32 v178, 31, v34
	s_cbranch_scc1 .LBB0_1317
	v_bitop3_b32 v18, v178, v34, s76 bitop3:0x36
	v_lshrrev_b32_e32 v19, 21, v18
	v_add_u32_e32 v19, v19, v172
	v_and_b32_e32 v20, 0x7ff, v19
	v_lshrrev_b32_e32 v19, 3, v19
	v_bitop3_b32 v19, v19, v20, 28 bitop3:0x6c
	v_lshl_add_u32 v19, v19, 2, v40
	ds_add_u32 v19, v186
	v_ashrrev_i32_e32 v19, 31, v35
	v_bitop3_b32 v19, v19, v35, s76 bitop3:0x36
	v_lshrrev_b32_e32 v20, 21, v19
	v_add_u32_e32 v20, v20, v172
	v_and_b32_e32 v21, 0x7ff, v20
	v_lshrrev_b32_e32 v20, 3, v20
	v_bitop3_b32 v20, v20, v21, 28 bitop3:0x6c
	v_lshl_add_u32 v20, v20, 2, v40
	ds_add_u32 v20, v186
	v_ashrrev_i32_e32 v20, 31, v32
	v_bitop3_b32 v20, v20, v32, s76 bitop3:0x36
	v_lshrrev_b32_e32 v21, 21, v20
	v_add_u32_e32 v21, v21, v172
	v_and_b32_e32 v22, 0x7ff, v21
	v_lshrrev_b32_e32 v21, 3, v21
	v_bitop3_b32 v21, v21, v22, 28 bitop3:0x6c
	v_lshl_add_u32 v21, v21, 2, v40
	ds_add_u32 v21, v186
	v_ashrrev_i32_e32 v21, 31, v33
	v_bitop3_b32 v23, v21, v33, s76 bitop3:0x36
	v_lshrrev_b32_e32 v21, 21, v23
	v_add_u32_e32 v21, v21, v172
	v_and_b32_e32 v22, 0x7ff, v21
	v_lshrrev_b32_e32 v21, 3, v21
	v_bitop3_b32 v21, v21, v22, 28 bitop3:0x6c
	v_lshl_add_u32 v21, v21, 2, v40
	ds_add_u32 v21, v186
	s_mov_b64 s[10:11], 0
	v_mov_b32_e32 v25, 0
	v_mov_b32_e32 v24, 0
	v_mov_b32_e32 v22, 0
	v_mov_b32_e32 v21, 0
	s_mov_b64 s[8:9], 0
	s_mov_b64 vcc, vcc
	s_cbranch_vccz .LBB0_1299
	v_ashrrev_i32_e32 v21, 31, v30
	v_bitop3_b32 v21, v21, v30, s76 bitop3:0x36
	v_lshrrev_b32_e32 v22, 21, v21
	v_add_u32_e32 v22, v22, v172
	v_and_b32_e32 v24, 0x7ff, v22
	v_lshrrev_b32_e32 v22, 3, v22
	v_bitop3_b32 v22, v22, v24, 28 bitop3:0x6c
	v_lshl_add_u32 v22, v22, 2, v40
	ds_add_u32 v22, v186
	v_ashrrev_i32_e32 v22, 31, v31
	v_bitop3_b32 v22, v22, v31, s76 bitop3:0x36
	v_lshrrev_b32_e32 v24, 21, v22
	v_add_u32_e32 v24, v24, v172
	v_and_b32_e32 v25, 0x7ff, v24
	v_lshrrev_b32_e32 v24, 3, v24
	v_bitop3_b32 v24, v24, v25, 28 bitop3:0x6c
	v_lshl_add_u32 v24, v24, 2, v40
	ds_add_u32 v24, v186
	v_ashrrev_i32_e32 v24, 31, v28
	v_bitop3_b32 v24, v24, v28, s76 bitop3:0x36
	v_lshrrev_b32_e32 v25, 21, v24
	v_add_u32_e32 v25, v25, v172
	v_and_b32_e32 v177, 0x7ff, v25
	v_lshrrev_b32_e32 v25, 3, v25
	v_bitop3_b32 v25, v25, v177, 28 bitop3:0x6c
	v_lshl_add_u32 v25, v25, 2, v40
	ds_add_u32 v25, v186
	v_ashrrev_i32_e32 v25, 31, v29
	v_bitop3_b32 v177, v25, v29, s76 bitop3:0x36
	s_mov_b64 s[8:9], -1
	v_mov_b32_e32 v25, v177
